# static priority: waves 4-7 raised in the attention/recurrence-pass-1 phase, waves 0-3 in the other phases (except the scan)
# speedup vs baseline: 1.0043x; 1.0012x over previous
.Lsp_gemm:
	v_readfirstlane_b32 s100, v206
	s_nop 3
	s_lshr_b32 s100, s100, 8
	s_cmp_eq_u32 s11, 1
	s_cselect_b32 s101, 1, 0
	s_cmp_lg_u32 s100, s101
	s_cbranch_scc1 .Lsp_done
	s_setprio 3
